# v36: v34 + static s_setprio 1 for waves 4-7 (the staggered half) for the whole GEMM phases, reset at the phase latch
# baseline (speedup 1.0000x reference)
; __global__ void __launch_bounds__(512, 1) mega_kernel(Params p) {
;     ...
;   for (int ph = p.phase_lo; ph <= p.phase_hi; ++ph) {
.LBB0_5:
	s_setprio 0
	s_add_i32 s0, s26, 1
	s_cmp_ge_i32 s26, s27
	s_mov_b32 s26, s0
	s_cbranch_scc1 .LBB0_594

; template <int GP> DI void gemm_phase(const Params& p, int l, int which, char* smem, int wv) {
;     ...
;   unsigned voffA[2];
; #pragma unroll
;   for (int i = 0; i < 2; ++i) { int R, C; stage_rc(tid * 16 + i * 8192, R, C); voffA[i] = (unsigned)(R * K + C) * 2u; }
;   auto voffB = [&](int i, int hf, bool m32) -> unsigned {
;     int t2 = tid; asm volatile("" : "+v"(t2));
;     int R, C; stage_rc(t2 * 16 + i * 8192, R, C);
;     const int swc = R >> 5, sn = (R >> 4) & 1, sfq = (R >> 2) & 3, sj = R & 3;
;     const int c = m32 ? ((swc >> 1) * 128 + (swc & 1) * 64 + hf * 32 + sfq * 8 + sn * 4 + sj)
;                       : ((swc >> 1) * 128 + hf * 64 + (swc & 1) * 32 + sfq * 8 + sn * 4 + sj);
;     return (unsigned)(c * K + C) * 2u;
;   };
;     ...
;   int ct = next_unit((blockIdx.x >> 3) - nbx, cmt, cnt_, ck0, cnk);
;   if (ct < 0) return;
.LBB0_128:
	s_cmp_lt_i32 s37, 0
	s_cbranch_scc1 .LBB0_159
	v_lshl_add_u32 v164, s35, 6, v2
	v_bfe_i32 v4, v164, 27, 1
	v_lshlrev_b32_e32 v0, 4, v164
	v_lshrrev_b32_e32 v4, 22, v4
	v_ashrrev_i32_e32 v3, 31, v164
	v_add_u32_e32 v4, v0, v4
	v_lshrrev_b32_e32 v3, 26, v3
	v_and_b32_e32 v4, 0xfffffc00, v4
	v_add_u32_e32 v3, v164, v3
	v_sub_u32_e32 v4, v0, v4
	v_ashrrev_i32_e32 v3, 6, v3
	v_lshrrev_b32_e32 v5, 4, v4
	v_bitop3_b32 v5, v5, v4, 32 bitop3:0x6c
	v_lshlrev_b32_e32 v4, 3, v3
	v_and_b32_e32 v6, 0xffff0, v4
	v_ashrrev_i32_e32 v4, 31, v5
	v_lshrrev_b32_e32 v4, 26, v4
	v_add_u32_e32 v7, v5, v4
	v_ashrrev_i32_e32 v4, 6, v7
	v_and_b32_e32 v7, 0xc0, v7
	v_sub_u32_e32 v5, v5, v7
	v_lshlrev_b32_e32 v8, 5, v3
	v_ashrrev_i16_sdwa v5, v231, sext(v5) dst_sel:DWORD dst_unused:UNUSED_PAD src0_sel:DWORD src1_sel:BYTE_0
	v_and_b32_e32 v8, 32, v8
	v_bfe_i32 v5, v5, 0, 16
	v_add_u32_e32 v7, v8, v5
	v_add_lshl_u32 v6, v4, v6, 12
	v_add_u32_e32 v0, 0x2000, v0
	v_lshl_add_u32 v130, v7, 1, v6
	v_ashrrev_i32_e32 v6, 31, v0
	v_lshrrev_b32_e32 v6, 22, v6
	v_add_u32_e32 v6, v0, v6
	v_ashrrev_i32_e32 v6, 10, v6
	v_mul_i32_i24_e32 v7, 0x400, v6
	v_sub_u32_e32 v0, v0, v7
	v_lshrrev_b32_e32 v7, 4, v0
	v_bitop3_b32 v0, v7, v0, 32 bitop3:0x6c
	v_lshlrev_b32_e32 v7, 3, v6
	v_and_b32_e32 v9, 0xffff0, v7
	v_ashrrev_i32_e32 v7, 31, v0
	v_lshrrev_b32_e32 v7, 26, v7
	v_add_u32_e32 v8, v0, v7
	v_ashrrev_i32_e32 v7, 6, v8
	v_and_b32_e32 v8, 0xc0, v8
	v_sub_u32_e32 v0, v0, v8
	v_lshlrev_b32_e32 v10, 5, v6
	v_ashrrev_i16_sdwa v0, v231, sext(v0) dst_sel:DWORD dst_unused:UNUSED_PAD src0_sel:DWORD src1_sel:BYTE_0
	v_and_b32_e32 v10, 32, v10
	v_bfe_i32 v8, v0, 0, 16
	v_add_u32_e32 v0, v10, v8
	v_add_lshl_u32 v9, v7, v9, 12
	v_lshl_add_u32 v132, v0, 1, v9
	v_mov_b32_e32 v0, v164
	s_mov_b32 s17, 0x40000
	v_ashrrev_i32_e32 v10, 31, v0
	v_lshrrev_b32_e32 v10, 26, v10
	v_lshlrev_b32_e32 v9, 4, v0
	v_add_u32_e32 v10, v0, v10
	v_bfe_i32 v0, v0, 27, 1
	v_lshrrev_b32_e32 v0, 22, v0
	v_add_u32_e32 v0, v9, v0
	v_and_b32_e32 v0, 0xfffffc00, v0
	v_sub_u32_e32 v0, v9, v0
	v_lshrrev_b32_e32 v9, 4, v0
	v_bitop3_b32 v0, v9, v0, 32 bitop3:0x6c
	v_ashrrev_i32_e32 v11, 31, v0
	v_ashrrev_i32_e32 v10, 6, v10
	v_lshrrev_b32_e32 v11, 26, v11
	v_lshlrev_b32_e32 v9, 3, v10
	v_add_u32_e32 v11, v0, v11
	v_and_b32_e32 v9, -16, v9
	v_ashrrev_i32_e32 v12, 6, v11
	v_add_u32_e32 v9, v12, v9
	v_lshlrev_b32_e32 v13, 1, v9
	v_and_b32_e32 v11, 0xc0, v11
	v_and_b32_e32 v13, 0xfff80, v13
	v_sub_u32_e32 v0, v0, v11
	v_and_or_b32 v13, v9, 32, v13
	v_lshlrev_b32_e32 v14, 1, v12
	v_lshrrev_b32_e32 v9, 2, v9
	v_lshlrev_b32_e32 v10, 5, v10
	v_ashrrev_i16_sdwa v0, v231, sext(v0) dst_sel:DWORD dst_unused:UNUSED_PAD src0_sel:DWORD src1_sel:BYTE_0
	v_and_b32_e32 v11, 3, v12
	v_and_b32_e32 v9, 4, v9
	v_and_b32_e32 v10, 32, v10
	v_bfe_i32 v0, v0, 0, 16
	v_and_or_b32 v11, v14, 24, v11
	v_or3_b32 v9, v11, v9, v13
	v_add_lshl_u32 v0, v10, v0, 1
	v_lshl_add_u32 v0, v9, 12, v0
	v_mov_b32_e32 v9, v164
	v_readlane_b32 s40, v253, 21
	v_ashrrev_i32_e32 v11, 31, v9
	v_lshrrev_b32_e32 v11, 26, v11
	v_lshlrev_b32_e32 v10, 4, v9
	v_add_u32_e32 v11, v9, v11
	v_bfe_i32 v9, v9, 27, 1
	v_lshrrev_b32_e32 v9, 22, v9
	v_add_u32_e32 v9, v10, v9
	v_and_b32_e32 v9, 0xfffffc00, v9
	v_sub_u32_e32 v9, v10, v9
	v_lshrrev_b32_e32 v10, 4, v9
	v_bitop3_b32 v9, v10, v9, 32 bitop3:0x6c
	v_ashrrev_i32_e32 v12, 31, v9
	v_ashrrev_i32_e32 v11, 6, v11
	v_lshrrev_b32_e32 v12, 26, v12
	v_lshlrev_b32_e32 v10, 3, v11
	v_add_u32_e32 v12, v9, v12
	v_and_b32_e32 v10, -16, v10
	v_ashrrev_i32_e32 v13, 6, v12
	v_add_u32_e32 v10, v13, v10
	v_lshlrev_b32_e32 v15, 1, v13
	v_lshrrev_b32_e32 v16, 2, v10
	v_and_b32_e32 v12, 0xc0, v12
	v_lshlrev_b32_e32 v14, 1, v10
	v_and_b32_e32 v15, 24, v15
	v_and_b32_e32 v16, 4, v16
	v_sub_u32_e32 v9, v9, v12
	v_and_b32_e32 v14, 0xfff80, v14
	v_lshlrev_b32_e32 v11, 5, v11
	v_ashrrev_i16_sdwa v9, v231, sext(v9) dst_sel:DWORD dst_unused:UNUSED_PAD src0_sel:DWORD src1_sel:BYTE_0
	v_and_or_b32 v12, v13, 3, v16
	v_and_or_b32 v10, v10, 32, v15
	v_and_b32_e32 v11, 32, v11
	v_bfe_i32 v9, v9, 0, 16
	v_or3_b32 v10, v10, v14, v12
	v_lshlrev_b32_e32 v10, 12, v10
; #define G_STAGE(bufoff, gbase, voff) do { _Pragma("unroll") for (int _i = 0; _i < 2; ++_i) \
;     __builtin_amdgcn_global_load_lds((const unsigned*)((const char*)(gbase) + (voff)[_i]), (LAS unsigned*)(lds + (bufoff) + ldsw + _i * 8192), 16, 0, 0); } while (0)
; #define G_BAR __builtin_amdgcn_s_barrier()
; template <int GP> DI void gemm_phase(const Params& p, int l, int which, char* smem, int wv) {
;     ...
;   for (int i = 0; i < 2; ++i) { int R, C; stage_rc(tid * 16 + i * 8192, R, C); voffA[i] = (unsigned)(R * K + C) * 2u; }
;   auto voffB = [&](int i, int hf, bool m32) -> unsigned {
;     int t2 = tid; asm volatile("" : "+v"(t2));
;     int R, C; stage_rc(t2 * 16 + i * 8192, R, C);
;     const int swc = R >> 5, sn = (R >> 4) & 1, sfq = (R >> 2) & 3, sj = R & 3;
;     const int c = m32 ? ((swc >> 1) * 128 + (swc & 1) * 64 + hf * 32 + sfq * 8 + sn * 4 + sj)
;                       : ((swc >> 1) * 128 + hf * 64 + (swc & 1) * 32 + sfq * 8 + sn * 4 + sj);
;     return (unsigned)(c * K + C) * 2u;
;   };
;     ...
;   const char* cA = (const char*)Aglob + (size_t)cmt * tstep + (size_t)ck0 * 2;
;   const char* cB = (const char*)Wt + (size_t)cnt_ * tstep + (size_t)ck0 * 2;
;   bool c32 = (!which) && (cnt_ < 4);
;   unsigned vb0[2], vb1[2];
; #pragma unroll
;   for (int i = 0; i < 2; ++i) { vb0[i] = voffB(i, 0, c32); vb1[i] = voffB(i, 1, c32); }
;   G_STAGE(G_SB(0, 0), cB, vb0); G_STAGE(G_SA(0, 0), cA, voffA); G_STAGE(G_SB(0, 1), cB, vb1); G_STAGE(G_SA(0, 1), cA + hstep, voffA);
;   if (wr == 1) G_BAR;
	v_add_lshl_u32 v9, v11, v9, 1
	v_add3_u32 v134, v9, v10, s17
	v_mov_b32_e32 v9, v164
	s_ashr_i32 s10, s35, 2
	v_lshl_add_u32 v9, v9, 4, v230
	v_ashrrev_i32_e32 v10, 31, v9
	v_lshrrev_b32_e32 v10, 22, v10
	v_add_u32_e32 v10, v9, v10
	v_ashrrev_i32_e32 v10, 10, v10
	v_mul_i32_i24_e32 v11, 0x400, v10
	v_sub_u32_e32 v9, v9, v11
	v_lshrrev_b32_e32 v11, 4, v9
	v_bitop3_b32 v9, v11, v9, 32 bitop3:0x6c
	v_ashrrev_i32_e32 v12, 31, v9
	v_lshrrev_b32_e32 v12, 26, v12
	v_lshlrev_b32_e32 v11, 3, v10
	v_add_u32_e32 v12, v9, v12
	v_and_b32_e32 v11, -16, v11
	v_ashrrev_i32_e32 v13, 6, v12
	v_add_u32_e32 v11, v13, v11
	v_lshlrev_b32_e32 v14, 1, v11
	v_and_b32_e32 v12, 0xc0, v12
	v_and_b32_e32 v14, 0xfff80, v14
	v_sub_u32_e32 v9, v9, v12
	v_and_or_b32 v14, v11, 32, v14
	v_lshlrev_b32_e32 v15, 1, v13
	v_lshrrev_b32_e32 v11, 2, v11
	v_lshlrev_b32_e32 v10, 5, v10
	v_ashrrev_i16_sdwa v9, v231, sext(v9) dst_sel:DWORD dst_unused:UNUSED_PAD src0_sel:DWORD src1_sel:BYTE_0
	v_and_b32_e32 v12, 3, v13
	v_and_b32_e32 v11, 4, v11
	v_and_b32_e32 v10, 32, v10
	v_bfe_i32 v9, v9, 0, 16
	v_and_or_b32 v12, v15, 24, v12
	v_or3_b32 v11, v12, v11, v14
	v_add_lshl_u32 v9, v10, v9, 1
	v_lshl_add_u32 v136, v11, 12, v9
	v_mov_b32_e32 v9, v164
	s_lshl_b32 s38, s35, 10
	v_lshl_add_u32 v9, v9, 4, v230
	v_ashrrev_i32_e32 v10, 31, v9
	v_lshrrev_b32_e32 v10, 22, v10
	v_add_u32_e32 v10, v9, v10
	s_lshl_b64 s[6:7], s[86:87], 23
	v_readlane_b32 s50, v253, 31
	v_ashrrev_i32_e32 v10, 10, v10
	v_readlane_b32 s51, v253, 32
	s_add_u32 s39, s50, s6
	v_mul_i32_i24_e32 v11, 0x400, v10
	s_addc_u32 s40, s51, s7
	s_ashr_i32 s3, s2, 31
	s_ashr_i32 s1, s0, 31
	s_ashr_i32 s5, s4, 31
	v_sub_u32_e32 v9, v9, v11
	s_lshl_b64 s[6:7], s[2:3], 20
	s_lshl_b64 s[8:9], s[0:1], 1
	s_lshl_b64 s[12:13], s[4:5], 20
	v_lshrrev_b32_e32 v11, 4, v9
	s_add_u32 s1, s39, s12
	v_bitop3_b32 v9, v11, v9, 32 bitop3:0x6c
	s_addc_u32 s3, s40, s13
	v_ashrrev_i32_e32 v12, 31, v9
	v_lshrrev_b32_e32 v12, 26, v12
	s_add_u32 s5, s56, s6
	v_lshlrev_b32_e32 v11, 3, v10
	v_add_u32_e32 v12, v9, v12
	s_addc_u32 s11, s57, s7
	v_and_b32_e32 v11, -16, v11
	v_ashrrev_i32_e32 v13, 6, v12
	s_add_u32 s6, s1, s8
	v_add_u32_e32 v11, v13, v11
	s_addc_u32 s7, s3, s9
	s_add_i32 s1, s38, 0x10000
	v_lshlrev_b32_e32 v15, 1, v13
	v_lshrrev_b32_e32 v16, 2, v11
	v_and_b32_e32 v12, 0xc0, v12
	s_mov_b32 m0, s1
	s_add_i32 s3, s38, 0x12000
	v_lshlrev_b32_e32 v14, 1, v11
	v_and_b32_e32 v15, 24, v15
	v_and_b32_e32 v16, 4, v16
	v_sub_u32_e32 v9, v9, v12
	global_load_lds_dwordx4 v0, s[6:7]
	s_mov_b32 m0, s3
	s_add_u32 s8, s5, s8
	v_readlane_b32 s41, v253, 22
	v_readlane_b32 s42, v253, 23
	v_and_b32_e32 v14, 0xfff80, v14
	v_lshlrev_b32_e32 v10, 5, v10
	v_ashrrev_i16_sdwa v9, v231, sext(v9) dst_sel:DWORD dst_unused:UNUSED_PAD src0_sel:DWORD src1_sel:BYTE_0
	v_and_or_b32 v12, v13, 3, v16
	v_and_or_b32 v11, v11, 32, v15
	global_load_lds_dwordx4 v136, s[6:7]
	s_addc_u32 s9, s11, s9
	s_mov_b32 m0, s38
	s_add_i32 s5, s38, 0x2000
	v_and_b32_e32 v10, 32, v10
	v_bfe_i32 v9, v9, 0, 16
	v_or3_b32 v11, v11, v14, v12
	global_load_lds_dwordx4 v130, s[8:9]
	s_mov_b32 m0, s5
	s_add_i32 s41, s38, 0x14000
	s_add_i32 s42, s38, 0x16000
	v_readlane_b32 s43, v253, 24
	v_lshlrev_b32_e32 v11, 12, v11
	v_add_lshl_u32 v9, v10, v9, 1
	global_load_lds_dwordx4 v132, s[8:9]
	s_mov_b32 m0, s41
	s_add_u32 s12, s8, 0x80000
	v_readlane_b32 s44, v253, 25
	v_add3_u32 v154, v9, v11, s17
	global_load_lds_dwordx4 v134, s[6:7]
	s_mov_b32 m0, s42
	s_addc_u32 s13, s9, 0
	s_add_i32 s43, s38, 0x4000
	global_load_lds_dwordx4 v154, s[6:7]
	s_mov_b32 m0, s43
	s_add_i32 s44, s38, 0x6000
	global_load_lds_dwordx4 v130, s[12:13]
	s_mov_b32 m0, s44
	s_cmp_lg_u32 s10, 1
	global_load_lds_dwordx4 v132, s[12:13]
	v_readlane_b32 s14, v253, 63
	v_readlane_b32 s15, v254, 10
	v_readlane_b32 s16, v254, 3
	v_readlane_b32 s45, v253, 26
	v_readlane_b32 s46, v253, 27
	v_readlane_b32 s47, v253, 28
	v_readlane_b32 s48, v253, 29
	v_readlane_b32 s49, v253, 30
	v_readlane_b32 s52, v253, 33
	v_readlane_b32 s53, v253, 34
	v_readlane_b32 s54, v253, 35
	v_readlane_b32 s55, v253, 36
	s_cbranch_scc1 .LBB0_131
	s_setprio 1
	s_barrier

; #define G_STAGE(bufoff, gbase, voff) do { _Pragma("unroll") for (int _i = 0; _i < 2; ++_i) \
;     __builtin_amdgcn_global_load_lds((const unsigned*)((const char*)(gbase) + (voff)[_i]), (LAS unsigned*)(lds + (bufoff) + ldsw + _i * 8192), 16, 0, 0); } while (0)
; #define G_BAR __builtin_amdgcn_s_barrier()
; template <int GP> DI void gemm_phase(const Params& p, int l, int which, char* smem, int wv) {
;     ...
;   for (int i = 0; i < 2; ++i) { int R, C; stage_rc(tid * 16 + i * 8192, R, C); voffA[i] = (unsigned)(R * K + C) * 2u; }
;   auto voffB = [&](int i, int hf, bool m32) -> unsigned {
;     int t2 = tid; asm volatile("" : "+v"(t2));
;     int R, C; stage_rc(t2 * 16 + i * 8192, R, C);
;     const int swc = R >> 5, sn = (R >> 4) & 1, sfq = (R >> 2) & 3, sj = R & 3;
;     const int c = m32 ? ((swc >> 1) * 128 + (swc & 1) * 64 + hf * 32 + sfq * 8 + sn * 4 + sj)
;                       : ((swc >> 1) * 128 + hf * 64 + (swc & 1) * 32 + sfq * 8 + sn * 4 + sj);
;     return (unsigned)(c * K + C) * 2u;
;   };
;     ...
;   const char* cA = (const char*)Aglob + (size_t)cmt * tstep + (size_t)ck0 * 2;
;   const char* cB = (const char*)Wt + (size_t)cnt_ * tstep + (size_t)ck0 * 2;
;   bool c32 = (!which) && (cnt_ < 4);
;   unsigned vb0[2], vb1[2];
; #pragma unroll
;   for (int i = 0; i < 2; ++i) { vb0[i] = voffB(i, 0, c32); vb1[i] = voffB(i, 1, c32); }
;   G_STAGE(G_SB(0, 0), cB, vb0); G_STAGE(G_SA(0, 0), cA, voffA); G_STAGE(G_SB(0, 1), cB, vb1); G_STAGE(G_SA(0, 1), cA + hstep, voffA);
;   if (wr == 1) G_BAR;
.LBB0_182:
	v_lshlrev_b32_e32 v15, 6, v5
	v_lshlrev_b32_e32 v14, 1, v5
	v_lshrrev_b32_e32 v7, 2, v7
	v_sub_u32_e32 v4, v4, v15
	v_and_b32_e32 v14, 24, v14
	v_and_b32_e32 v7, 4, v7
	v_lshlrev_b32_e32 v3, 5, v3
	v_ashrrev_i16_sdwa v4, v231, sext(v4) dst_sel:DWORD dst_unused:UNUSED_PAD src0_sel:DWORD src1_sel:BYTE_0
	v_and_b32_e32 v5, 3, v5
	v_and_b32_e32 v3, 32, v3
	v_bfe_i32 v4, v4, 0, 16
	v_or3_b32 v5, v14, v5, v7
	v_add_u32_e32 v5, v5, v6
	v_add_lshl_u32 v3, v3, v4, 1
	v_lshl_add_u32 v130, v5, 12, v3
	v_lshl_add_u32 v3, v9, 4, v230
	v_ashrrev_i32_e32 v4, 31, v3
	v_lshrrev_b32_e32 v4, 22, v4
	v_add_u32_e32 v4, v3, v4
	v_ashrrev_i32_e32 v4, 10, v4
	v_mul_i32_i24_e32 v5, 0x400, v4
	v_sub_u32_e32 v3, v3, v5
	v_lshrrev_b32_e32 v5, 4, v3
	v_bitop3_b32 v3, v5, v3, 32 bitop3:0x6c
	v_ashrrev_i32_e32 v6, 31, v3
	v_lshrrev_b32_e32 v6, 26, v6
	v_lshlrev_b32_e32 v5, 3, v4
	v_add_u32_e32 v6, v3, v6
	v_and_b32_e32 v5, -16, v5
	v_ashrrev_i32_e32 v7, 6, v6
	v_add_u32_e32 v5, v7, v5
	v_and_b32_e32 v6, 0xc0, v6
	v_lshlrev_b32_e32 v9, 1, v5
	v_and_b32_e32 v14, 32, v5
	v_sub_u32_e32 v3, v3, v6
	v_and_or_b32 v14, v9, s5, v14
	v_and_b32_e32 v9, 0xfffc0, v9
	v_lshlrev_b32_e32 v4, 5, v4
	v_ashrrev_i16_sdwa v3, v231, sext(v3) dst_sel:DWORD dst_unused:UNUSED_PAD src0_sel:DWORD src1_sel:BYTE_0
	v_cndmask_b32_e64 v9, v14, v9, s[26:27]
	v_lshlrev_b32_e32 v14, 1, v7
	v_lshrrev_b32_e32 v5, 2, v5
	v_and_b32_e32 v4, 32, v4
	v_bfe_i32 v3, v3, 0, 16
	v_and_b32_e32 v6, 3, v7
	v_and_b32_e32 v5, 4, v5
	v_and_or_b32 v6, v14, 24, v6
	v_add_lshl_u32 v3, v4, v3, 1
	v_ashrrev_i32_e32 v4, 31, v0
	v_or3_b32 v5, v6, v5, v9
	v_lshrrev_b32_e32 v4, 26, v4
	v_lshl_add_u32 v136, v5, 12, v3
	v_lshlrev_b32_e32 v3, 4, v0
	v_add_u32_e32 v4, v0, v4
	v_bfe_i32 v0, v0, 27, 1
	v_lshrrev_b32_e32 v0, 22, v0
	v_add_u32_e32 v0, v3, v0
	v_and_b32_e32 v0, 0xfffffc00, v0
	v_sub_u32_e32 v0, v3, v0
	v_lshrrev_b32_e32 v3, 4, v0
	v_bitop3_b32 v0, v3, v0, 32 bitop3:0x6c
	v_ashrrev_i32_e32 v5, 31, v0
	v_ashrrev_i32_e32 v4, 6, v4
	v_lshrrev_b32_e32 v5, 26, v5
	v_lshlrev_b32_e32 v3, 3, v4
	v_add_u32_e32 v5, v0, v5
	v_and_b32_e32 v3, -16, v3
	v_ashrrev_i32_e32 v6, 6, v5
	v_add_u32_e32 v3, v6, v3
	v_and_b32_e32 v5, 0xc0, v5
	v_lshlrev_b32_e32 v7, 1, v3
	v_and_b32_e32 v9, 32, v3
	v_sub_u32_e32 v0, v0, v5
	v_and_or_b32 v9, v7, s5, v9
	v_and_b32_e32 v7, 0xfffc0, v7
	v_lshlrev_b32_e32 v4, 5, v4
	v_ashrrev_i16_sdwa v0, v231, sext(v0) dst_sel:DWORD dst_unused:UNUSED_PAD src0_sel:DWORD src1_sel:BYTE_0
	v_cndmask_b32_e64 v7, v9, v7, s[26:27]
	v_lshlrev_b32_e32 v9, 1, v6
	v_lshrrev_b32_e32 v3, 2, v3
	v_and_b32_e32 v4, 32, v4
	v_bfe_i32 v0, v0, 0, 16
	v_and_b32_e32 v5, 3, v6
	v_and_b32_e32 v3, 4, v3
	v_and_or_b32 v5, v9, 24, v5
	v_add_lshl_u32 v0, v4, v0, 1
	v_bfe_i32 v4, v208, 27, 1
	v_or3_b32 v3, v5, v3, v7
	v_lshlrev_b32_e32 v6, 4, v208
	v_lshrrev_b32_e32 v4, 22, v4
	v_lshl_add_u32 v0, v3, 12, v0
	v_ashrrev_i32_e32 v3, 31, v208
	v_add_u32_e32 v4, v6, v4
	v_lshrrev_b32_e32 v3, 26, v3
	v_and_b32_e32 v4, 0xfffffc00, v4
	v_add_u32_e32 v3, v208, v3
	v_sub_u32_e32 v4, v6, v4
	v_ashrrev_i32_e32 v3, 6, v3
	v_lshrrev_b32_e32 v5, 4, v4
	v_bitop3_b32 v5, v5, v4, 32 bitop3:0x6c
	v_lshlrev_b32_e32 v4, 3, v3
	v_and_b32_e32 v7, 0xffff0, v4
	v_ashrrev_i32_e32 v4, 31, v5
	v_lshrrev_b32_e32 v4, 26, v4
	v_add_u32_e32 v9, v5, v4
	v_ashrrev_i32_e32 v4, 6, v9
	v_and_b32_e32 v9, 0xc0, v9
	v_sub_u32_e32 v5, v5, v9
	v_lshlrev_b32_e32 v14, 5, v3
	v_ashrrev_i16_sdwa v5, v231, sext(v5) dst_sel:DWORD dst_unused:UNUSED_PAD src0_sel:DWORD src1_sel:BYTE_0
	v_and_b32_e32 v14, 32, v14
	v_bfe_i32 v5, v5, 0, 16
	v_add_u32_e32 v9, v14, v5
	v_add_lshl_u32 v7, v4, v7, 12
	v_lshl_add_u32 v132, v9, 1, v7
	v_add_u32_e32 v7, 0x2000, v6
	v_ashrrev_i32_e32 v6, 31, v7
	v_lshrrev_b32_e32 v6, 22, v6
	v_add_u32_e32 v6, v7, v6
	v_ashrrev_i32_e32 v6, 10, v6
	v_mul_i32_i24_e32 v9, 0x400, v6
	v_sub_u32_e32 v7, v7, v9
	v_lshrrev_b32_e32 v9, 4, v7
	v_readlane_b32 s36, v253, 21
	v_bitop3_b32 v9, v9, v7, 32 bitop3:0x6c
	v_lshlrev_b32_e32 v7, 3, v6
	s_mul_i32 s1, s86, 0x1c00000
	v_readlane_b32 s44, v253, 29
	v_and_b32_e32 v14, 0xffff0, v7
	v_ashrrev_i32_e32 v7, 31, v9
	s_mul_hi_i32 s0, s86, 0x1c00000
	v_readlane_b32 s45, v253, 30
	s_add_u32 s56, s44, s1
	v_lshrrev_b32_e32 v7, 26, v7
	s_addc_u32 s57, s45, s0
	s_ashr_i32 s23, s22, 31
	s_ashr_i32 s25, s24, 31
	v_add_u32_e32 v15, v9, v7
	s_lshl_b64 s[2:3], s[22:23], 20
	s_lshl_b64 s[0:1], s[24:25], 20
	v_ashrrev_i32_e32 v7, 6, v15
	v_and_b32_e32 v15, 0xc0, v15
	s_add_u32 s0, s56, s0
	v_sub_u32_e32 v9, v9, v15
	v_readlane_b32 s48, v253, 33
	s_addc_u32 s1, s57, s1
	s_ashr_i32 s5, s84, 2
	v_lshlrev_b32_e32 v16, 5, v6
	v_ashrrev_i16_sdwa v9, v231, sext(v9) dst_sel:DWORD dst_unused:UNUSED_PAD src0_sel:DWORD src1_sel:BYTE_0
	s_lshl_b32 s23, s84, 10
	v_readlane_b32 s49, v253, 34
	v_and_b32_e32 v16, 32, v16
	v_bfe_i32 v9, v9, 0, 16
	s_add_u32 s28, s48, s2
	v_add_u32_e32 v15, v16, v9
	v_add_lshl_u32 v14, v7, v14, 12
	s_addc_u32 s29, s49, s3
	s_add_i32 s25, s23, 0x10000
	v_lshl_add_u32 v134, v15, 1, v14
	v_lshlrev_b32_e32 v15, 6, v11
	s_mov_b32 m0, s25
	s_add_i32 s58, s23, 0x12000
	v_lshlrev_b32_e32 v14, 1, v11
	v_lshrrev_b32_e32 v12, 2, v12
	v_sub_u32_e32 v10, v10, v15
	global_load_lds_dwordx4 v0, s[0:1]
	s_mov_b32 m0, s58
	v_and_b32_e32 v14, 24, v14
	v_and_b32_e32 v12, 4, v12
	v_lshlrev_b32_e32 v8, 5, v8
	v_ashrrev_i16_sdwa v10, v231, sext(v10) dst_sel:DWORD dst_unused:UNUSED_PAD src0_sel:DWORD src1_sel:BYTE_0
	v_and_b32_e32 v11, 3, v11
	global_load_lds_dwordx4 v136, s[0:1]
	s_mov_b32 m0, s23
	s_add_i32 s59, s23, 0x2000
	v_and_b32_e32 v8, 32, v8
	v_bfe_i32 v10, v10, 0, 16
	v_or3_b32 v11, v14, v11, v12
	global_load_lds_dwordx4 v132, s[28:29]
	s_mov_b32 m0, s59
	s_add_i32 s60, s23, 0x14000
	s_add_i32 s61, s23, 0x16000
	v_add_u32_e32 v11, v11, v13
	v_add_lshl_u32 v8, v8, v10, 1
	global_load_lds_dwordx4 v134, s[28:29]
	s_mov_b32 m0, s60
	s_add_u32 s2, s28, 0x80000
	v_lshl_add_u32 v142, v11, 12, v8
	global_load_lds_dwordx4 v130, s[0:1]
	s_mov_b32 m0, s61
	s_addc_u32 s3, s29, 0
	s_add_i32 s62, s23, 0x4000
	global_load_lds_dwordx4 v142, s[0:1]
	s_mov_b32 m0, s62
	s_add_i32 s63, s23, 0x6000
	global_load_lds_dwordx4 v132, s[2:3]
	s_mov_b32 m0, s63
	s_cmp_lg_u32 s5, 1
	global_load_lds_dwordx4 v134, s[2:3]
	v_readlane_b32 s37, v253, 22
	v_readlane_b32 s38, v253, 23
	v_readlane_b32 s39, v253, 24
	v_readlane_b32 s40, v253, 25
	v_readlane_b32 s41, v253, 26
	v_readlane_b32 s42, v253, 27
	v_readlane_b32 s43, v253, 28
	v_readlane_b32 s46, v253, 31
	v_readlane_b32 s47, v253, 32
	v_readlane_b32 s50, v253, 35
	v_readlane_b32 s51, v253, 36
	s_cbranch_scc1 .LBB0_184
	s_setprio 1
	s_barrier
